# placement: every GEMM K-loop head padded to byte phase 0 mod 8 (one s_nop per pre-loop)
# baseline (speedup 1.0000x reference)
; template <class Epi, class Sched, bool HM = false>
; __device__ __forceinline__ void gemm_phase(PG8_LAS unsigned char* lds, const Gemm g, const Sched& S, const Epi& E) {
;     ...
;     f32x4 acc[2][2][4][2]; f32x4 accx[2];
; #pragma unroll
;     for (int a = 0; a < 2; ++a)
; #pragma unroll
;         for (int b = 0; b < 2; ++b)
; #pragma unroll
;             for (int m = 0; m < 4; ++m)
; #pragma unroll
;                 for (int n = 0; n < 2; ++n) acc[a][b][m][n] = (f32x4){0.f, 0.f, 0.f, 0.f};
;     accx[0] = (f32x4){0.f, 0.f, 0.f, 0.f}; accx[1] = accx[0];
.LBB0_253:
	s_add_u32 s95, s4, 0x100
	s_addc_u32 s38, s5, 0
	v_mov_b32_e32 v4, v3
	v_mov_b32_e32 v5, v3
	s_add_u32 s27, s6, 0x100
	v_mov_b32_e32 v2, v3
	v_mov_b32_e32 v22, 0
	v_mov_b64_e32 v[20:21], v[4:5]
	v_mov_b64_e32 v[16:17], v[4:5]
	s_addc_u32 s39, s7, 0
	s_mov_b32 s22, 0
	s_mov_b32 s23, -2
	v_mov_b64_e32 v[18:19], v[2:3]
	v_mov_b64_e32 v[14:15], v[2:3]
	v_mov_b32_e32 v23, v22
	v_mov_b32_e32 v24, v22
	v_mov_b32_e32 v25, v22
	v_mov_b32_e32 v26, v22
	v_mov_b32_e32 v27, v22
	v_mov_b32_e32 v28, v22
	v_mov_b32_e32 v29, v22
	v_mov_b32_e32 v30, v22
	v_mov_b32_e32 v31, v22
	v_mov_b32_e32 v32, v22
	v_mov_b32_e32 v33, v22
	v_mov_b32_e32 v38, v22
	v_mov_b32_e32 v39, v22
	v_mov_b32_e32 v40, v22
	v_mov_b32_e32 v41, v22
	v_mov_b32_e32 v46, v22
	v_mov_b32_e32 v47, v22
	v_mov_b32_e32 v48, v22
	v_mov_b32_e32 v49, v22
	v_mov_b32_e32 v54, v22
	v_mov_b32_e32 v55, v22
	v_mov_b32_e32 v56, v22
	v_mov_b32_e32 v57, v22
	v_mov_b32_e32 v62, v22
	v_mov_b32_e32 v63, v22
	v_mov_b32_e32 v64, v22
	v_mov_b32_e32 v65, v22
	v_mov_b32_e32 v70, v22
	v_mov_b32_e32 v71, v22
	v_mov_b32_e32 v72, v22
	v_mov_b32_e32 v73, v22
	v_mov_b32_e32 v34, v22
	v_mov_b32_e32 v35, v22
	v_mov_b32_e32 v36, v22
	v_mov_b32_e32 v37, v22
	v_mov_b32_e32 v42, v22
	v_mov_b32_e32 v43, v22
	v_mov_b32_e32 v44, v22
	v_mov_b32_e32 v45, v22
	v_mov_b32_e32 v50, v22
	v_mov_b32_e32 v51, v22
	v_mov_b32_e32 v52, v22
	v_mov_b32_e32 v53, v22
	v_mov_b32_e32 v58, v22
	v_mov_b32_e32 v59, v22
	v_mov_b32_e32 v60, v22
	v_mov_b32_e32 v61, v22
	v_mov_b32_e32 v66, v22
	v_mov_b32_e32 v67, v22
	v_mov_b32_e32 v68, v22
	v_mov_b32_e32 v69, v22
	v_mov_b32_e32 v74, v22
	v_mov_b32_e32 v75, v22
	v_mov_b32_e32 v76, v22
	v_mov_b32_e32 v77, v22
	v_mov_b32_e32 v78, v22
	v_mov_b32_e32 v79, v22
	v_mov_b32_e32 v80, v22
	v_mov_b32_e32 v81, v22
	v_mov_b32_e32 v82, v22
	v_mov_b32_e32 v83, v22
	v_mov_b32_e32 v84, v22
	v_mov_b32_e32 v85, v22
	v_mov_b32_e32 v86, v22
	v_mov_b32_e32 v87, v22
	v_mov_b32_e32 v88, v22
	v_mov_b32_e32 v89, v22
	v_mov_b32_e32 v90, v22
	v_mov_b32_e32 v91, v22
	v_mov_b32_e32 v92, v22
	v_mov_b32_e32 v93, v22
	v_mov_b32_e32 v94, v22
	v_mov_b32_e32 v95, v22
	v_mov_b32_e32 v96, v22
	v_mov_b32_e32 v97, v22
	v_mov_b32_e32 v102, v22
	v_mov_b32_e32 v103, v22
	v_mov_b32_e32 v104, v22
	v_mov_b32_e32 v105, v22
	v_mov_b32_e32 v110, v22
	v_mov_b32_e32 v111, v22
	v_mov_b32_e32 v112, v22
	v_mov_b32_e32 v113, v22
	v_mov_b32_e32 v118, v22
	v_mov_b32_e32 v119, v22
	v_mov_b32_e32 v120, v22
	v_mov_b32_e32 v121, v22
	v_mov_b32_e32 v126, v22
	v_mov_b32_e32 v127, v22
	v_mov_b32_e32 v128, v22
	v_mov_b32_e32 v129, v22
	v_mov_b32_e32 v134, v22
	v_mov_b32_e32 v135, v22
	v_mov_b32_e32 v136, v22
	v_mov_b32_e32 v137, v22
	v_mov_b32_e32 v98, v22
	v_mov_b32_e32 v99, v22
	v_mov_b32_e32 v100, v22
	v_mov_b32_e32 v101, v22
	v_mov_b32_e32 v106, v22
	v_mov_b32_e32 v107, v22
	v_mov_b32_e32 v108, v22
	v_mov_b32_e32 v109, v22
	v_mov_b32_e32 v114, v22
	v_mov_b32_e32 v115, v22
	v_mov_b32_e32 v116, v22
	v_mov_b32_e32 v117, v22
	v_mov_b32_e32 v122, v22
	v_mov_b32_e32 v123, v22
	v_mov_b32_e32 v124, v22
	v_mov_b32_e32 v125, v22
	v_mov_b32_e32 v130, v22
	v_mov_b32_e32 v131, v22
	v_mov_b32_e32 v132, v22
	v_mov_b32_e32 v133, v22
	v_mov_b32_e32 v138, v22
	v_mov_b32_e32 v139, v22
	v_mov_b32_e32 v140, v22
	v_mov_b32_e32 v141, v22
	v_mov_b32_e32 v142, v22
	v_mov_b32_e32 v143, v22
	v_mov_b32_e32 v144, v22
	v_mov_b32_e32 v145, v22
	v_mov_b32_e32 v146, v22
	v_mov_b32_e32 v147, v22
	v_mov_b32_e32 v148, v22
	v_mov_b32_e32 v149, v22
	s_nop 0
	s_branch .LBB0_256

; template <class Epi, class Sched, bool HM = false>
; __device__ __forceinline__ void gemm_phase(PG8_LAS unsigned char* lds, const Gemm g, const Sched& S, const Epi& E) {
;     ...
;     f32x4 acc[2][2][4][2]; f32x4 accx[2];
; #pragma unroll
;     for (int a = 0; a < 2; ++a)
; #pragma unroll
;         for (int b = 0; b < 2; ++b)
; #pragma unroll
;             for (int m = 0; m < 4; ++m)
; #pragma unroll
;                 for (int n = 0; n < 2; ++n) acc[a][b][m][n] = (f32x4){0.f, 0.f, 0.f, 0.f};
;     accx[0] = (f32x4){0.f, 0.f, 0.f, 0.f}; accx[1] = accx[0];
.LBB0_984:
	s_add_u32 s89, s4, 0x100
	s_addc_u32 s90, s5, 0
	v_mov_b32_e32 v4, v3
	v_mov_b32_e32 v5, v3
	s_add_u32 s27, s6, 0x100
	v_mov_b32_e32 v2, v3
	v_mov_b32_e32 v22, 0
	v_mov_b64_e32 v[20:21], v[4:5]
	v_mov_b64_e32 v[16:17], v[4:5]
	s_addc_u32 s82, s7, 0
	s_mov_b32 s22, 0
	s_mov_b32 s23, -2
	v_mov_b64_e32 v[18:19], v[2:3]
	v_mov_b64_e32 v[14:15], v[2:3]
	v_mov_b32_e32 v23, v22
	v_mov_b32_e32 v24, v22
	v_mov_b32_e32 v25, v22
	v_mov_b32_e32 v26, v22
	v_mov_b32_e32 v27, v22
	v_mov_b32_e32 v28, v22
	v_mov_b32_e32 v29, v22
	v_mov_b32_e32 v30, v22
	v_mov_b32_e32 v31, v22
	v_mov_b32_e32 v32, v22
	v_mov_b32_e32 v33, v22
	v_mov_b32_e32 v38, v22
	v_mov_b32_e32 v39, v22
	v_mov_b32_e32 v40, v22
	v_mov_b32_e32 v41, v22
	v_mov_b32_e32 v46, v22
	v_mov_b32_e32 v47, v22
	v_mov_b32_e32 v48, v22
	v_mov_b32_e32 v49, v22
	v_mov_b32_e32 v54, v22
	v_mov_b32_e32 v55, v22
	v_mov_b32_e32 v56, v22
	v_mov_b32_e32 v57, v22
	v_mov_b32_e32 v62, v22
	v_mov_b32_e32 v63, v22
	v_mov_b32_e32 v64, v22
	v_mov_b32_e32 v65, v22
	v_mov_b32_e32 v70, v22
	v_mov_b32_e32 v71, v22
	v_mov_b32_e32 v72, v22
	v_mov_b32_e32 v73, v22
	v_mov_b32_e32 v34, v22
	v_mov_b32_e32 v35, v22
	v_mov_b32_e32 v36, v22
	v_mov_b32_e32 v37, v22
	v_mov_b32_e32 v42, v22
	v_mov_b32_e32 v43, v22
	v_mov_b32_e32 v44, v22
	v_mov_b32_e32 v45, v22
	v_mov_b32_e32 v50, v22
	v_mov_b32_e32 v51, v22
	v_mov_b32_e32 v52, v22
	v_mov_b32_e32 v53, v22
	v_mov_b32_e32 v58, v22
	v_mov_b32_e32 v59, v22
	v_mov_b32_e32 v60, v22
	v_mov_b32_e32 v61, v22
	v_mov_b32_e32 v66, v22
	v_mov_b32_e32 v67, v22
	v_mov_b32_e32 v68, v22
	v_mov_b32_e32 v69, v22
	v_mov_b32_e32 v74, v22
	v_mov_b32_e32 v75, v22
	v_mov_b32_e32 v76, v22
	v_mov_b32_e32 v77, v22
	v_mov_b32_e32 v78, v22
	v_mov_b32_e32 v79, v22
	v_mov_b32_e32 v80, v22
	v_mov_b32_e32 v81, v22
	v_mov_b32_e32 v82, v22
	v_mov_b32_e32 v83, v22
	v_mov_b32_e32 v84, v22
	v_mov_b32_e32 v85, v22
	v_mov_b32_e32 v86, v22
	v_mov_b32_e32 v87, v22
	v_mov_b32_e32 v88, v22
	v_mov_b32_e32 v89, v22
	v_mov_b32_e32 v90, v22
	v_mov_b32_e32 v91, v22
	v_mov_b32_e32 v92, v22
	v_mov_b32_e32 v93, v22
	v_mov_b32_e32 v94, v22
	v_mov_b32_e32 v95, v22
	v_mov_b32_e32 v96, v22
	v_mov_b32_e32 v97, v22
	v_mov_b32_e32 v102, v22
	v_mov_b32_e32 v103, v22
	v_mov_b32_e32 v104, v22
	v_mov_b32_e32 v105, v22
	v_mov_b32_e32 v110, v22
	v_mov_b32_e32 v111, v22
	v_mov_b32_e32 v112, v22
	v_mov_b32_e32 v113, v22
	v_mov_b32_e32 v118, v22
	v_mov_b32_e32 v119, v22
	v_mov_b32_e32 v120, v22
	v_mov_b32_e32 v121, v22
	v_mov_b32_e32 v126, v22
	v_mov_b32_e32 v127, v22
	v_mov_b32_e32 v128, v22
	v_mov_b32_e32 v129, v22
	v_mov_b32_e32 v134, v22
	v_mov_b32_e32 v135, v22
	v_mov_b32_e32 v136, v22
	v_mov_b32_e32 v137, v22
	v_mov_b32_e32 v98, v22
	v_mov_b32_e32 v99, v22
	v_mov_b32_e32 v100, v22
	v_mov_b32_e32 v101, v22
	v_mov_b32_e32 v106, v22
	v_mov_b32_e32 v107, v22
	v_mov_b32_e32 v108, v22
	v_mov_b32_e32 v109, v22
	v_mov_b32_e32 v114, v22
	v_mov_b32_e32 v115, v22
	v_mov_b32_e32 v116, v22
	v_mov_b32_e32 v117, v22
	v_mov_b32_e32 v122, v22
	v_mov_b32_e32 v123, v22
	v_mov_b32_e32 v124, v22
	v_mov_b32_e32 v125, v22
	v_mov_b32_e32 v130, v22
	v_mov_b32_e32 v131, v22
	v_mov_b32_e32 v132, v22
	v_mov_b32_e32 v133, v22
	v_mov_b32_e32 v138, v22
	v_mov_b32_e32 v139, v22
	v_mov_b32_e32 v140, v22
	v_mov_b32_e32 v141, v22
	v_mov_b32_e32 v142, v22
	v_mov_b32_e32 v143, v22
	v_mov_b32_e32 v144, v22
	v_mov_b32_e32 v145, v22
	v_mov_b32_e32 v146, v22
	v_mov_b32_e32 v147, v22
	v_mov_b32_e32 v148, v22
	v_mov_b32_e32 v149, v22
	s_nop 0
	s_branch .LBB0_987

; template <class Epi, class Sched, bool HM = false>
; __device__ __forceinline__ void gemm_phase(PG8_LAS unsigned char* lds, const Gemm g, const Sched& S, const Epi& E) {
;     ...
;     f32x4 acc[2][2][4][2]; f32x4 accx[2];
; #pragma unroll
;     for (int a = 0; a < 2; ++a)
; #pragma unroll
;         for (int b = 0; b < 2; ++b)
; #pragma unroll
;             for (int m = 0; m < 4; ++m)
; #pragma unroll
;                 for (int n = 0; n < 2; ++n) acc[a][b][m][n] = (f32x4){0.f, 0.f, 0.f, 0.f};
;     accx[0] = (f32x4){0.f, 0.f, 0.f, 0.f}; accx[1] = accx[0];
.LBB0_1161:
	s_add_u32 s15, s0, 0x100
	s_addc_u32 s16, s1, 0
	s_add_u32 s17, s4, 0x100
	v_mov_b32_e32 v4, 0
	s_addc_u32 s18, s5, 0
	s_mov_b32 s19, -2
	s_mov_b32 s22, 0
	v_mov_b32_e32 v5, v4
	v_mov_b32_e32 v6, v4
	v_mov_b32_e32 v7, v4
	v_mov_b32_e32 v12, v4
	v_mov_b32_e32 v13, v4
	v_mov_b32_e32 v14, v4
	v_mov_b32_e32 v15, v4
	v_mov_b32_e32 v20, v4
	v_mov_b32_e32 v21, v4
	v_mov_b32_e32 v22, v4
	v_mov_b32_e32 v23, v4
	v_mov_b32_e32 v28, v4
	v_mov_b32_e32 v29, v4
	v_mov_b32_e32 v30, v4
	v_mov_b32_e32 v31, v4
	v_mov_b32_e32 v36, v4
	v_mov_b32_e32 v37, v4
	v_mov_b32_e32 v38, v4
	v_mov_b32_e32 v39, v4
	v_mov_b32_e32 v44, v4
	v_mov_b32_e32 v45, v4
	v_mov_b32_e32 v46, v4
	v_mov_b32_e32 v47, v4
	v_mov_b32_e32 v52, v4
	v_mov_b32_e32 v53, v4
	v_mov_b32_e32 v54, v4
	v_mov_b32_e32 v55, v4
	v_mov_b32_e32 v60, v4
	v_mov_b32_e32 v61, v4
	v_mov_b32_e32 v62, v4
	v_mov_b32_e32 v63, v4
	v_mov_b32_e32 v8, v4
	v_mov_b32_e32 v9, v4
	v_mov_b32_e32 v10, v4
	v_mov_b32_e32 v11, v4
	v_mov_b32_e32 v16, v4
	v_mov_b32_e32 v17, v4
	v_mov_b32_e32 v18, v4
	v_mov_b32_e32 v19, v4
	v_mov_b32_e32 v24, v4
	v_mov_b32_e32 v25, v4
	v_mov_b32_e32 v26, v4
	v_mov_b32_e32 v27, v4
	v_mov_b32_e32 v32, v4
	v_mov_b32_e32 v33, v4
	v_mov_b32_e32 v34, v4
	v_mov_b32_e32 v35, v4
	v_mov_b32_e32 v40, v4
	v_mov_b32_e32 v41, v4
	v_mov_b32_e32 v42, v4
	v_mov_b32_e32 v43, v4
	v_mov_b32_e32 v48, v4
	v_mov_b32_e32 v49, v4
	v_mov_b32_e32 v50, v4
	v_mov_b32_e32 v51, v4
	v_mov_b32_e32 v56, v4
	v_mov_b32_e32 v57, v4
	v_mov_b32_e32 v58, v4
	v_mov_b32_e32 v59, v4
	v_mov_b32_e32 v64, v4
	v_mov_b32_e32 v65, v4
	v_mov_b32_e32 v66, v4
	v_mov_b32_e32 v67, v4
	v_mov_b32_e32 v68, v4
	v_mov_b32_e32 v69, v4
	v_mov_b32_e32 v70, v4
	v_mov_b32_e32 v71, v4
	v_mov_b32_e32 v76, v4
	v_mov_b32_e32 v77, v4
	v_mov_b32_e32 v78, v4
	v_mov_b32_e32 v79, v4
	v_mov_b32_e32 v84, v4
	v_mov_b32_e32 v85, v4
	v_mov_b32_e32 v86, v4
	v_mov_b32_e32 v87, v4
	v_mov_b32_e32 v92, v4
	v_mov_b32_e32 v93, v4
	v_mov_b32_e32 v94, v4
	v_mov_b32_e32 v95, v4
	v_mov_b32_e32 v100, v4
	v_mov_b32_e32 v101, v4
	v_mov_b32_e32 v102, v4
	v_mov_b32_e32 v103, v4
	v_mov_b32_e32 v108, v4
	v_mov_b32_e32 v109, v4
	v_mov_b32_e32 v110, v4
	v_mov_b32_e32 v111, v4
	v_mov_b32_e32 v116, v4
	v_mov_b32_e32 v117, v4
	v_mov_b32_e32 v118, v4
	v_mov_b32_e32 v119, v4
	v_mov_b32_e32 v124, v4
	v_mov_b32_e32 v125, v4
	v_mov_b32_e32 v126, v4
	v_mov_b32_e32 v127, v4
	v_mov_b32_e32 v72, v4
	v_mov_b32_e32 v73, v4
	v_mov_b32_e32 v74, v4
	v_mov_b32_e32 v75, v4
	v_mov_b32_e32 v80, v4
	v_mov_b32_e32 v81, v4
	v_mov_b32_e32 v82, v4
	v_mov_b32_e32 v83, v4
	v_mov_b32_e32 v88, v4
	v_mov_b32_e32 v89, v4
	v_mov_b32_e32 v90, v4
	v_mov_b32_e32 v91, v4
	v_mov_b32_e32 v96, v4
	v_mov_b32_e32 v97, v4
	v_mov_b32_e32 v98, v4
	v_mov_b32_e32 v99, v4
	v_mov_b32_e32 v104, v4
	v_mov_b32_e32 v105, v4
	v_mov_b32_e32 v106, v4
	v_mov_b32_e32 v107, v4
	v_mov_b32_e32 v112, v4
	v_mov_b32_e32 v113, v4
	v_mov_b32_e32 v114, v4
	v_mov_b32_e32 v115, v4
	v_mov_b32_e32 v120, v4
	v_mov_b32_e32 v121, v4
	v_mov_b32_e32 v122, v4
	v_mov_b32_e32 v123, v4
	v_mov_b32_e32 v128, v4
	v_mov_b32_e32 v129, v4
	v_mov_b32_e32 v130, v4
	v_mov_b32_e32 v131, v4
	s_nop 0

; template <class Epi, class Sched, bool HM = false>
; __device__ __forceinline__ void gemm_phase(PG8_LAS unsigned char* lds, const Gemm g, const Sched& S, const Epi& E) {
;     ...
;     f32x4 acc[2][2][4][2]; f32x4 accx[2];
; #pragma unroll
;     for (int a = 0; a < 2; ++a)
; #pragma unroll
;         for (int b = 0; b < 2; ++b)
; #pragma unroll
;             for (int m = 0; m < 4; ++m)
; #pragma unroll
;                 for (int n = 0; n < 2; ++n) acc[a][b][m][n] = (f32x4){0.f, 0.f, 0.f, 0.f};
;     accx[0] = (f32x4){0.f, 0.f, 0.f, 0.f}; accx[1] = accx[0];
.LBB0_1186:
	s_add_u32 s27, s4, 0x100
	s_addc_u32 s52, s5, 0
	s_add_u32 s58, s6, 0x100
	v_mov_b32_e32 v4, 0
	s_addc_u32 s59, s7, 0
	s_mov_b32 s60, -2
	s_mov_b32 s61, 0
	v_mov_b32_e32 v5, v4
	v_mov_b32_e32 v6, v4
	v_mov_b32_e32 v7, v4
	v_mov_b32_e32 v12, v4
	v_mov_b32_e32 v13, v4
	v_mov_b32_e32 v14, v4
	v_mov_b32_e32 v15, v4
	v_mov_b32_e32 v20, v4
	v_mov_b32_e32 v21, v4
	v_mov_b32_e32 v22, v4
	v_mov_b32_e32 v23, v4
	v_mov_b32_e32 v28, v4
	v_mov_b32_e32 v29, v4
	v_mov_b32_e32 v30, v4
	v_mov_b32_e32 v31, v4
	v_mov_b32_e32 v36, v4
	v_mov_b32_e32 v37, v4
	v_mov_b32_e32 v38, v4
	v_mov_b32_e32 v39, v4
	v_mov_b32_e32 v44, v4
	v_mov_b32_e32 v45, v4
	v_mov_b32_e32 v46, v4
	v_mov_b32_e32 v47, v4
	v_mov_b32_e32 v52, v4
	v_mov_b32_e32 v53, v4
	v_mov_b32_e32 v54, v4
	v_mov_b32_e32 v55, v4
	v_mov_b32_e32 v60, v4
	v_mov_b32_e32 v61, v4
	v_mov_b32_e32 v62, v4
	v_mov_b32_e32 v63, v4
	v_mov_b32_e32 v8, v4
	v_mov_b32_e32 v9, v4
	v_mov_b32_e32 v10, v4
	v_mov_b32_e32 v11, v4
	v_mov_b32_e32 v16, v4
	v_mov_b32_e32 v17, v4
	v_mov_b32_e32 v18, v4
	v_mov_b32_e32 v19, v4
	v_mov_b32_e32 v24, v4
	v_mov_b32_e32 v25, v4
	v_mov_b32_e32 v26, v4
	v_mov_b32_e32 v27, v4
	v_mov_b32_e32 v32, v4
	v_mov_b32_e32 v33, v4
	v_mov_b32_e32 v34, v4
	v_mov_b32_e32 v35, v4
	v_mov_b32_e32 v40, v4
	v_mov_b32_e32 v41, v4
	v_mov_b32_e32 v42, v4
	v_mov_b32_e32 v43, v4
	v_mov_b32_e32 v48, v4
	v_mov_b32_e32 v49, v4
	v_mov_b32_e32 v50, v4
	v_mov_b32_e32 v51, v4
	v_mov_b32_e32 v56, v4
	v_mov_b32_e32 v57, v4
	v_mov_b32_e32 v58, v4
	v_mov_b32_e32 v59, v4
	v_mov_b32_e32 v64, v4
	v_mov_b32_e32 v65, v4
	v_mov_b32_e32 v66, v4
	v_mov_b32_e32 v67, v4
	s_nop 0

; template <class Epi, class Sched, bool HM = false>
; __device__ __forceinline__ void gemm_phase(PG8_LAS unsigned char* lds, const Gemm g, const Sched& S, const Epi& E) {
;     ...
;     f32x4 acc[2][2][4][2]; f32x4 accx[2];
; #pragma unroll
;     for (int a = 0; a < 2; ++a)
; #pragma unroll
;         for (int b = 0; b < 2; ++b)
; #pragma unroll
;             for (int m = 0; m < 4; ++m)
; #pragma unroll
;                 for (int n = 0; n < 2; ++n) acc[a][b][m][n] = (f32x4){0.f, 0.f, 0.f, 0.f};
;     accx[0] = (f32x4){0.f, 0.f, 0.f, 0.f}; accx[1] = accx[0];
.LBB0_1266:
	s_add_u32 s88, s4, 0x100
	s_addc_u32 s89, s5, 0
	v_mov_b32_e32 v4, v3
	v_mov_b32_e32 v5, v3
	s_add_u32 s27, s6, 0x100
	v_mov_b32_e32 v2, v3
	v_mov_b32_e32 v22, 0
	v_mov_b64_e32 v[20:21], v[4:5]
	v_mov_b64_e32 v[16:17], v[4:5]
	s_addc_u32 s82, s7, 0
	s_mov_b32 s22, 0
	s_mov_b32 s23, -2
	v_mov_b64_e32 v[18:19], v[2:3]
	v_mov_b64_e32 v[14:15], v[2:3]
	v_mov_b32_e32 v23, v22
	v_mov_b32_e32 v24, v22
	v_mov_b32_e32 v25, v22
	v_mov_b32_e32 v26, v22
	v_mov_b32_e32 v27, v22
	v_mov_b32_e32 v28, v22
	v_mov_b32_e32 v29, v22
	v_mov_b32_e32 v30, v22
	v_mov_b32_e32 v31, v22
	v_mov_b32_e32 v32, v22
	v_mov_b32_e32 v33, v22
	v_mov_b32_e32 v38, v22
	v_mov_b32_e32 v39, v22
	v_mov_b32_e32 v40, v22
	v_mov_b32_e32 v41, v22
	v_mov_b32_e32 v46, v22
	v_mov_b32_e32 v47, v22
	v_mov_b32_e32 v48, v22
	v_mov_b32_e32 v49, v22
	v_mov_b32_e32 v54, v22
	v_mov_b32_e32 v55, v22
	v_mov_b32_e32 v56, v22
	v_mov_b32_e32 v57, v22
	v_mov_b32_e32 v62, v22
	v_mov_b32_e32 v63, v22
	v_mov_b32_e32 v64, v22
	v_mov_b32_e32 v65, v22
	v_mov_b32_e32 v70, v22
	v_mov_b32_e32 v71, v22
	v_mov_b32_e32 v72, v22
	v_mov_b32_e32 v73, v22
	v_mov_b32_e32 v34, v22
	v_mov_b32_e32 v35, v22
	v_mov_b32_e32 v36, v22
	v_mov_b32_e32 v37, v22
	v_mov_b32_e32 v42, v22
	v_mov_b32_e32 v43, v22
	v_mov_b32_e32 v44, v22
	v_mov_b32_e32 v45, v22
	v_mov_b32_e32 v50, v22
	v_mov_b32_e32 v51, v22
	v_mov_b32_e32 v52, v22
	v_mov_b32_e32 v53, v22
	v_mov_b32_e32 v58, v22
	v_mov_b32_e32 v59, v22
	v_mov_b32_e32 v60, v22
	v_mov_b32_e32 v61, v22
	v_mov_b32_e32 v66, v22
	v_mov_b32_e32 v67, v22
	v_mov_b32_e32 v68, v22
	v_mov_b32_e32 v69, v22
	v_mov_b32_e32 v74, v22
	v_mov_b32_e32 v75, v22
	v_mov_b32_e32 v76, v22
	v_mov_b32_e32 v77, v22
	v_mov_b32_e32 v78, v22
	v_mov_b32_e32 v79, v22
	v_mov_b32_e32 v80, v22
	v_mov_b32_e32 v81, v22
	v_mov_b32_e32 v82, v22
	v_mov_b32_e32 v83, v22
	v_mov_b32_e32 v84, v22
	v_mov_b32_e32 v85, v22
	v_mov_b32_e32 v86, v22
	v_mov_b32_e32 v87, v22
	v_mov_b32_e32 v88, v22
	v_mov_b32_e32 v89, v22
	v_mov_b32_e32 v90, v22
	v_mov_b32_e32 v91, v22
	v_mov_b32_e32 v92, v22
	v_mov_b32_e32 v93, v22
	v_mov_b32_e32 v94, v22
	v_mov_b32_e32 v95, v22
	v_mov_b32_e32 v96, v22
	v_mov_b32_e32 v97, v22
	v_mov_b32_e32 v102, v22
	v_mov_b32_e32 v103, v22
	v_mov_b32_e32 v104, v22
	v_mov_b32_e32 v105, v22
	v_mov_b32_e32 v110, v22
	v_mov_b32_e32 v111, v22
	v_mov_b32_e32 v112, v22
	v_mov_b32_e32 v113, v22
	v_mov_b32_e32 v118, v22
	v_mov_b32_e32 v119, v22
	v_mov_b32_e32 v120, v22
	v_mov_b32_e32 v121, v22
	v_mov_b32_e32 v126, v22
	v_mov_b32_e32 v127, v22
	v_mov_b32_e32 v128, v22
	v_mov_b32_e32 v129, v22
	v_mov_b32_e32 v134, v22
	v_mov_b32_e32 v135, v22
	v_mov_b32_e32 v136, v22
	v_mov_b32_e32 v137, v22
	v_mov_b32_e32 v98, v22
	v_mov_b32_e32 v99, v22
	v_mov_b32_e32 v100, v22
	v_mov_b32_e32 v101, v22
	v_mov_b32_e32 v106, v22
	v_mov_b32_e32 v107, v22
	v_mov_b32_e32 v108, v22
	v_mov_b32_e32 v109, v22
	v_mov_b32_e32 v114, v22
	v_mov_b32_e32 v115, v22
	v_mov_b32_e32 v116, v22
	v_mov_b32_e32 v117, v22
	v_mov_b32_e32 v122, v22
	v_mov_b32_e32 v123, v22
	v_mov_b32_e32 v124, v22
	v_mov_b32_e32 v125, v22
	v_mov_b32_e32 v130, v22
	v_mov_b32_e32 v131, v22
	v_mov_b32_e32 v132, v22
	v_mov_b32_e32 v133, v22
	v_mov_b32_e32 v138, v22
	v_mov_b32_e32 v139, v22
	v_mov_b32_e32 v140, v22
	v_mov_b32_e32 v141, v22
	v_mov_b32_e32 v142, v22
	v_mov_b32_e32 v143, v22
	v_mov_b32_e32 v144, v22
	v_mov_b32_e32 v145, v22
	v_mov_b32_e32 v146, v22
	v_mov_b32_e32 v147, v22
	v_mov_b32_e32 v148, v22
	v_mov_b32_e32 v149, v22
	s_nop 0
	s_branch .LBB0_1269
